# attention far blocks: surplus wait states trimmed (s_nop 1 -> s_nop 0 after bf16 pack before MFMA; no pad after permlane32_swap)
# baseline (speedup 1.0000x reference)
.LBB0_586:
	s_andn2_b64 vcc, exec, s[8:9]
	v_mov_b32_e32 v251, 0
	s_cbranch_vccnz .LBB0_588
	v_max3_f32 v188, v64, v65, s77
	v_max3_f32 v188, v66, v67, v188
	v_max3_f32 v188, v68, v69, v188
	v_max3_f32 v188, v70, v71, v188
	v_max3_f32 v188, v72, v73, v188
	v_max3_f32 v188, v74, v75, v188
	v_max3_f32 v188, v76, v77, v188
	v_max3_f32 v188, v78, v79, v188
	v_max3_f32 v188, v80, v81, v188
	v_max3_f32 v188, v82, v83, v188
	v_max3_f32 v188, v84, v85, v188
	v_max3_f32 v188, v86, v87, v188
	v_max3_f32 v188, v88, v89, v188
	v_max3_f32 v188, v90, v91, v188
	v_max3_f32 v188, v92, v93, v188
	v_max3_f32 v188, v94, v95, v188
	v_fmamk_f32 v189, v188, 0x3fb8aa3b, v247
	v_mov_b32_e32 v190, v189
	s_nop 1
	v_permlane32_swap_b32_e32 v190, v189
	v_max3_f32 v191, v250, v189, v190
	v_sub_f32_e32 v192, v250, v191
	v_exp_f32_e32 v194, v192
	v_cmp_gt_f32_e32 vcc, v191, v250
	v_sub_f32_e32 v192, v247, v191
	s_mul_i32 s8, s87, 0x5000
	v_add_u32_e32 v210, s8, v230
	ds_read_b64_tr_b16 v[198:199], v210 offset:34816
	ds_read_b64_tr_b16 v[200:201], v210 offset:37376
	ds_read_b64_tr_b16 v[202:203], v210 offset:34880
	ds_read_b64_tr_b16 v[204:205], v210 offset:37440
	ds_read_b64_tr_b16 v[206:207], v210 offset:34944
	ds_read_b64_tr_b16 v[208:209], v210 offset:37504
	ds_read_b64_tr_b16 v[250:251], v210 offset:35008
	ds_read_b64_tr_b16 v[252:253], v210 offset:37568
	s_cbranch_vccz .Lfar1_noresc
	v_pk_mul_f32 v[62:63], v[62:63], v[194:195] op_sel_hi:[1,0]
	v_pk_mul_f32 v[60:61], v[60:61], v[194:195] op_sel_hi:[1,0]
	v_pk_mul_f32 v[58:59], v[58:59], v[194:195] op_sel_hi:[1,0]
	v_pk_mul_f32 v[56:57], v[56:57], v[194:195] op_sel_hi:[1,0]
	v_pk_mul_f32 v[54:55], v[54:55], v[194:195] op_sel_hi:[1,0]
	v_pk_mul_f32 v[52:53], v[52:53], v[194:195] op_sel_hi:[1,0]
	v_pk_mul_f32 v[50:51], v[50:51], v[194:195] op_sel_hi:[1,0]
	v_pk_mul_f32 v[48:49], v[48:49], v[194:195] op_sel_hi:[1,0]
	v_pk_mul_f32 v[46:47], v[46:47], v[194:195] op_sel_hi:[1,0]
	v_pk_mul_f32 v[44:45], v[44:45], v[194:195] op_sel_hi:[1,0]
	v_pk_mul_f32 v[42:43], v[42:43], v[194:195] op_sel_hi:[1,0]
	v_pk_mul_f32 v[40:41], v[40:41], v[194:195] op_sel_hi:[1,0]
	v_pk_mul_f32 v[38:39], v[38:39], v[194:195] op_sel_hi:[1,0]
	v_pk_mul_f32 v[36:37], v[36:37], v[194:195] op_sel_hi:[1,0]
	v_pk_mul_f32 v[34:35], v[34:35], v[194:195] op_sel_hi:[1,0]
	v_pk_mul_f32 v[32:33], v[32:33], v[194:195] op_sel_hi:[1,0]
	v_pk_mul_f32 v[30:31], v[30:31], v[194:195] op_sel_hi:[1,0]
	v_pk_mul_f32 v[28:29], v[28:29], v[194:195] op_sel_hi:[1,0]
	v_pk_mul_f32 v[26:27], v[26:27], v[194:195] op_sel_hi:[1,0]
	v_pk_mul_f32 v[24:25], v[24:25], v[194:195] op_sel_hi:[1,0]
	v_pk_mul_f32 v[22:23], v[22:23], v[194:195] op_sel_hi:[1,0]
	v_pk_mul_f32 v[20:21], v[20:21], v[194:195] op_sel_hi:[1,0]
	v_pk_mul_f32 v[18:19], v[18:19], v[194:195] op_sel_hi:[1,0]
	v_pk_mul_f32 v[16:17], v[16:17], v[194:195] op_sel_hi:[1,0]
	v_pk_mul_f32 v[14:15], v[14:15], v[194:195] op_sel_hi:[1,0]
	v_pk_mul_f32 v[12:13], v[12:13], v[194:195] op_sel_hi:[1,0]
	v_pk_mul_f32 v[10:11], v[10:11], v[194:195] op_sel_hi:[1,0]
	v_pk_mul_f32 v[8:9], v[8:9], v[194:195] op_sel_hi:[1,0]
	v_pk_mul_f32 v[6:7], v[6:7], v[194:195] op_sel_hi:[1,0]
	v_pk_mul_f32 v[4:5], v[4:5], v[194:195] op_sel_hi:[1,0]
	v_pk_mul_f32 v[2:3], v[2:3], v[194:195] op_sel_hi:[1,0]
	v_pk_mul_f32 v[0:1], v[0:1], v[194:195] op_sel_hi:[1,0]
.Lfar1_noresc:
	v_fmamk_f32 v189, v64, 0x3fb8aa3b, v192
	v_exp_f32_e32 v180, v189
	v_fmamk_f32 v189, v65, 0x3fb8aa3b, v192
	v_exp_f32_e32 v181, v189
	v_fmamk_f32 v189, v66, 0x3fb8aa3b, v192
	v_exp_f32_e32 v182, v189
	v_fmamk_f32 v189, v67, 0x3fb8aa3b, v192
	v_exp_f32_e32 v183, v189
	v_fmamk_f32 v189, v68, 0x3fb8aa3b, v192
	v_exp_f32_e32 v184, v189
	v_fmamk_f32 v189, v69, 0x3fb8aa3b, v192
	v_exp_f32_e32 v185, v189
	v_fmamk_f32 v189, v70, 0x3fb8aa3b, v192
	v_exp_f32_e32 v186, v189
	v_fmamk_f32 v189, v71, 0x3fb8aa3b, v192
	v_exp_f32_e32 v187, v189
	v_cvt_pk_bf16_f32 v64, v180, v181
	v_cvt_pk_bf16_f32 v65, v182, v183
	v_cvt_pk_bf16_f32 v66, v184, v185
	v_cvt_pk_bf16_f32 v67, v186, v187
	s_nop 0
	s_waitcnt lgkmcnt(6)
	v_mfma_f32_32x32x16_bf16 v[48:63], v[198:201], v[64:67], v[48:63]
	ds_read_b64_tr_b16 v[198:199], v210 offset:39936
	ds_read_b64_tr_b16 v[200:201], v210 offset:42496
	v_add_f32_e32 v196, v180, v182
	v_add_f32_e32 v197, v181, v183
	v_add_f32_e32 v196, v196, v184
	v_add_f32_e32 v197, v197, v185
	v_add_f32_e32 v196, v196, v186
	v_add_f32_e32 v197, v197, v187
	v_fmamk_f32 v189, v72, 0x3fb8aa3b, v192
	v_exp_f32_e32 v180, v189
	v_fmamk_f32 v189, v73, 0x3fb8aa3b, v192
	v_exp_f32_e32 v181, v189
	s_waitcnt lgkmcnt(6)
	v_mfma_f32_32x32x16_bf16 v[32:47], v[202:205], v[64:67], v[32:47]
	ds_read_b64_tr_b16 v[202:203], v210 offset:40000
	ds_read_b64_tr_b16 v[204:205], v210 offset:42560
	v_fmamk_f32 v189, v74, 0x3fb8aa3b, v192
	v_exp_f32_e32 v182, v189
	v_fmamk_f32 v189, v75, 0x3fb8aa3b, v192
	v_exp_f32_e32 v183, v189
	s_waitcnt lgkmcnt(6)
	v_mfma_f32_32x32x16_bf16 v[16:31], v[206:209], v[64:67], v[16:31]
	ds_read_b64_tr_b16 v[206:207], v210 offset:40064
	ds_read_b64_tr_b16 v[208:209], v210 offset:42624
	v_fmamk_f32 v189, v76, 0x3fb8aa3b, v192
	v_exp_f32_e32 v184, v189
	v_fmamk_f32 v189, v77, 0x3fb8aa3b, v192
	v_exp_f32_e32 v185, v189
	s_waitcnt lgkmcnt(6)
	v_mfma_f32_32x32x16_bf16 v[0:15], v[250:253], v[64:67], v[0:15]
	ds_read_b64_tr_b16 v[250:251], v210 offset:40128
	ds_read_b64_tr_b16 v[252:253], v210 offset:42688
	v_fmamk_f32 v189, v78, 0x3fb8aa3b, v192
	v_exp_f32_e32 v186, v189
	v_fmamk_f32 v189, v79, 0x3fb8aa3b, v192
	v_exp_f32_e32 v187, v189
	v_cvt_pk_bf16_f32 v72, v180, v181
	v_cvt_pk_bf16_f32 v73, v182, v183
	v_cvt_pk_bf16_f32 v74, v184, v185
	v_cvt_pk_bf16_f32 v75, v186, v187
	s_nop 0
	s_waitcnt lgkmcnt(6)
	v_mfma_f32_32x32x16_bf16 v[48:63], v[198:201], v[72:75], v[48:63]
	ds_read_b64_tr_b16 v[198:199], v210 offset:45056
	ds_read_b64_tr_b16 v[200:201], v210 offset:47616
	v_add_f32_e32 v196, v196, v180
	v_add_f32_e32 v197, v197, v181
	v_add_f32_e32 v196, v196, v182
	v_add_f32_e32 v197, v197, v183
	v_add_f32_e32 v196, v196, v184
	v_add_f32_e32 v197, v197, v185
	v_add_f32_e32 v196, v196, v186
	v_add_f32_e32 v197, v197, v187
	v_fmamk_f32 v189, v80, 0x3fb8aa3b, v192
	v_exp_f32_e32 v180, v189
	v_fmamk_f32 v189, v81, 0x3fb8aa3b, v192
	v_exp_f32_e32 v181, v189
	s_waitcnt lgkmcnt(6)
	v_mfma_f32_32x32x16_bf16 v[32:47], v[202:205], v[72:75], v[32:47]
	ds_read_b64_tr_b16 v[202:203], v210 offset:45120
	ds_read_b64_tr_b16 v[204:205], v210 offset:47680
	v_fmamk_f32 v189, v82, 0x3fb8aa3b, v192
	v_exp_f32_e32 v182, v189
	v_fmamk_f32 v189, v83, 0x3fb8aa3b, v192
	v_exp_f32_e32 v183, v189
	s_waitcnt lgkmcnt(6)
	v_mfma_f32_32x32x16_bf16 v[16:31], v[206:209], v[72:75], v[16:31]
	ds_read_b64_tr_b16 v[206:207], v210 offset:45184
	ds_read_b64_tr_b16 v[208:209], v210 offset:47744
	v_fmamk_f32 v189, v84, 0x3fb8aa3b, v192
	v_exp_f32_e32 v184, v189
	v_fmamk_f32 v189, v85, 0x3fb8aa3b, v192
	v_exp_f32_e32 v185, v189
	s_waitcnt lgkmcnt(6)
	v_mfma_f32_32x32x16_bf16 v[0:15], v[250:253], v[72:75], v[0:15]
	ds_read_b64_tr_b16 v[250:251], v210 offset:45248
	ds_read_b64_tr_b16 v[252:253], v210 offset:47808
	v_fmamk_f32 v189, v86, 0x3fb8aa3b, v192
	v_exp_f32_e32 v186, v189
	v_fmamk_f32 v189, v87, 0x3fb8aa3b, v192
	v_exp_f32_e32 v187, v189
	v_cvt_pk_bf16_f32 v80, v180, v181
	v_cvt_pk_bf16_f32 v81, v182, v183
	v_cvt_pk_bf16_f32 v82, v184, v185
	v_cvt_pk_bf16_f32 v83, v186, v187
	s_nop 0
	s_waitcnt lgkmcnt(6)
	v_mfma_f32_32x32x16_bf16 v[48:63], v[198:201], v[80:83], v[48:63]
	ds_read_b64_tr_b16 v[198:199], v210 offset:50176
	ds_read_b64_tr_b16 v[200:201], v210 offset:52736
	v_add_f32_e32 v196, v196, v180
	v_add_f32_e32 v197, v197, v181
	v_add_f32_e32 v196, v196, v182
	v_add_f32_e32 v197, v197, v183
	v_add_f32_e32 v196, v196, v184
	v_add_f32_e32 v197, v197, v185
	v_add_f32_e32 v196, v196, v186
	v_add_f32_e32 v197, v197, v187
	v_fmamk_f32 v189, v88, 0x3fb8aa3b, v192
	v_exp_f32_e32 v180, v189
	v_fmamk_f32 v189, v89, 0x3fb8aa3b, v192
	v_exp_f32_e32 v181, v189
	s_waitcnt lgkmcnt(6)
	v_mfma_f32_32x32x16_bf16 v[32:47], v[202:205], v[80:83], v[32:47]
	ds_read_b64_tr_b16 v[202:203], v210 offset:50240
	ds_read_b64_tr_b16 v[204:205], v210 offset:52800
	v_fmamk_f32 v189, v90, 0x3fb8aa3b, v192
	v_exp_f32_e32 v182, v189
	v_fmamk_f32 v189, v91, 0x3fb8aa3b, v192
	v_exp_f32_e32 v183, v189
	s_waitcnt lgkmcnt(6)
	v_mfma_f32_32x32x16_bf16 v[16:31], v[206:209], v[80:83], v[16:31]
	ds_read_b64_tr_b16 v[206:207], v210 offset:50304
	ds_read_b64_tr_b16 v[208:209], v210 offset:52864
	v_fmamk_f32 v189, v92, 0x3fb8aa3b, v192
	v_exp_f32_e32 v184, v189
	v_fmamk_f32 v189, v93, 0x3fb8aa3b, v192
	v_exp_f32_e32 v185, v189
	s_waitcnt lgkmcnt(6)
	v_mfma_f32_32x32x16_bf16 v[0:15], v[250:253], v[80:83], v[0:15]
	ds_read_b64_tr_b16 v[250:251], v210 offset:50368
	ds_read_b64_tr_b16 v[252:253], v210 offset:52928
	v_fmamk_f32 v189, v94, 0x3fb8aa3b, v192
	v_exp_f32_e32 v186, v189
	v_fmamk_f32 v189, v95, 0x3fb8aa3b, v192
	v_exp_f32_e32 v187, v189
	v_cvt_pk_bf16_f32 v88, v180, v181
	v_cvt_pk_bf16_f32 v89, v182, v183
	v_cvt_pk_bf16_f32 v90, v184, v185
	v_cvt_pk_bf16_f32 v91, v186, v187
	s_nop 0
	s_waitcnt lgkmcnt(6)
	v_mfma_f32_32x32x16_bf16 v[48:63], v[198:201], v[88:91], v[48:63]
	v_add_f32_e32 v196, v196, v180
	v_add_f32_e32 v197, v197, v181
	v_add_f32_e32 v196, v196, v182
	v_add_f32_e32 v197, v197, v183
	v_add_f32_e32 v196, v196, v184
	v_add_f32_e32 v197, v197, v185
	v_add_f32_e32 v196, v196, v186
	v_add_f32_e32 v197, v197, v187
	s_waitcnt lgkmcnt(4)
	v_mfma_f32_32x32x16_bf16 v[32:47], v[202:205], v[88:91], v[32:47]
	s_waitcnt lgkmcnt(2)
	v_mfma_f32_32x32x16_bf16 v[16:31], v[206:209], v[88:91], v[16:31]
	s_waitcnt lgkmcnt(0)
	v_mfma_f32_32x32x16_bf16 v[0:15], v[250:253], v[88:91], v[0:15]
	v_add_f32_e32 v82, v196, v197
	v_mov_b32_e32 v80, v194
	v_mov_b32_e32 v81, v191
	s_branch .Lattn1_tail

.LBB0_609:
	s_andn2_b64 vcc, exec, s[54:55]
	v_mov_b32_e32 v195, 0
	s_cbranch_vccnz .LBB0_611
	v_max3_f32 v168, v64, v65, s77
	v_max3_f32 v168, v66, v67, v168
	v_max3_f32 v168, v68, v69, v168
	v_max3_f32 v168, v70, v71, v168
	v_max3_f32 v168, v72, v73, v168
	v_max3_f32 v168, v74, v75, v168
	v_max3_f32 v168, v76, v77, v168
	v_max3_f32 v168, v78, v79, v168
	v_max3_f32 v168, v80, v81, v168
	v_max3_f32 v168, v82, v83, v168
	v_max3_f32 v168, v84, v85, v168
	v_max3_f32 v168, v86, v87, v168
	v_max3_f32 v168, v88, v89, v168
	v_max3_f32 v168, v90, v91, v168
	v_max3_f32 v168, v92, v93, v168
	v_max3_f32 v168, v94, v95, v168
	v_fmamk_f32 v169, v168, 0x3fb8aa3b, v136
	v_mov_b32_e32 v170, v169
	s_nop 1
	v_permlane32_swap_b32_e32 v170, v169
	v_max3_f32 v193, v194, v169, v170
	v_sub_f32_e32 v172, v194, v193
	v_exp_f32_e32 v174, v172
	v_cmp_gt_f32_e32 vcc, v193, v194
	v_sub_f32_e32 v172, v136, v193
	s_mul_i32 s54, s85, 0x5000
	v_add_u32_e32 v177, s54, v230
	ds_read_b64_tr_b16 v[178:179], v177 offset:34816
	ds_read_b64_tr_b16 v[180:181], v177 offset:37376
	ds_read_b64_tr_b16 v[182:183], v177 offset:34880
	ds_read_b64_tr_b16 v[184:185], v177 offset:37440
	ds_read_b64_tr_b16 v[186:187], v177 offset:34944
	ds_read_b64_tr_b16 v[188:189], v177 offset:37504
	ds_read_b64_tr_b16 v[198:199], v177 offset:35008
	ds_read_b64_tr_b16 v[200:201], v177 offset:37568
	s_cbranch_vccz .Lfar2_noresc
	v_pk_mul_f32 v[62:63], v[62:63], v[174:175] op_sel_hi:[1,0]
	v_pk_mul_f32 v[60:61], v[60:61], v[174:175] op_sel_hi:[1,0]
	v_pk_mul_f32 v[58:59], v[58:59], v[174:175] op_sel_hi:[1,0]
	v_pk_mul_f32 v[56:57], v[56:57], v[174:175] op_sel_hi:[1,0]
	v_pk_mul_f32 v[54:55], v[54:55], v[174:175] op_sel_hi:[1,0]
	v_pk_mul_f32 v[52:53], v[52:53], v[174:175] op_sel_hi:[1,0]
	v_pk_mul_f32 v[50:51], v[50:51], v[174:175] op_sel_hi:[1,0]
	v_pk_mul_f32 v[48:49], v[48:49], v[174:175] op_sel_hi:[1,0]
	v_pk_mul_f32 v[46:47], v[46:47], v[174:175] op_sel_hi:[1,0]
	v_pk_mul_f32 v[44:45], v[44:45], v[174:175] op_sel_hi:[1,0]
	v_pk_mul_f32 v[42:43], v[42:43], v[174:175] op_sel_hi:[1,0]
	v_pk_mul_f32 v[40:41], v[40:41], v[174:175] op_sel_hi:[1,0]
	v_pk_mul_f32 v[38:39], v[38:39], v[174:175] op_sel_hi:[1,0]
	v_pk_mul_f32 v[36:37], v[36:37], v[174:175] op_sel_hi:[1,0]
	v_pk_mul_f32 v[34:35], v[34:35], v[174:175] op_sel_hi:[1,0]
	v_pk_mul_f32 v[32:33], v[32:33], v[174:175] op_sel_hi:[1,0]
	v_pk_mul_f32 v[30:31], v[30:31], v[174:175] op_sel_hi:[1,0]
	v_pk_mul_f32 v[28:29], v[28:29], v[174:175] op_sel_hi:[1,0]
	v_pk_mul_f32 v[26:27], v[26:27], v[174:175] op_sel_hi:[1,0]
	v_pk_mul_f32 v[24:25], v[24:25], v[174:175] op_sel_hi:[1,0]
	v_pk_mul_f32 v[22:23], v[22:23], v[174:175] op_sel_hi:[1,0]
	v_pk_mul_f32 v[20:21], v[20:21], v[174:175] op_sel_hi:[1,0]
	v_pk_mul_f32 v[18:19], v[18:19], v[174:175] op_sel_hi:[1,0]
	v_pk_mul_f32 v[16:17], v[16:17], v[174:175] op_sel_hi:[1,0]
	v_pk_mul_f32 v[14:15], v[14:15], v[174:175] op_sel_hi:[1,0]
	v_pk_mul_f32 v[12:13], v[12:13], v[174:175] op_sel_hi:[1,0]
	v_pk_mul_f32 v[10:11], v[10:11], v[174:175] op_sel_hi:[1,0]
	v_pk_mul_f32 v[8:9], v[8:9], v[174:175] op_sel_hi:[1,0]
	v_pk_mul_f32 v[6:7], v[6:7], v[174:175] op_sel_hi:[1,0]
	v_pk_mul_f32 v[4:5], v[4:5], v[174:175] op_sel_hi:[1,0]
	v_pk_mul_f32 v[2:3], v[2:3], v[174:175] op_sel_hi:[1,0]
	v_pk_mul_f32 v[0:1], v[0:1], v[174:175] op_sel_hi:[1,0]
.Lfar2_noresc:
	v_fmamk_f32 v169, v64, 0x3fb8aa3b, v172
	v_exp_f32_e32 v160, v169
	v_fmamk_f32 v169, v65, 0x3fb8aa3b, v172
	v_exp_f32_e32 v161, v169
	v_fmamk_f32 v169, v66, 0x3fb8aa3b, v172
	v_exp_f32_e32 v162, v169
	v_fmamk_f32 v169, v67, 0x3fb8aa3b, v172
	v_exp_f32_e32 v163, v169
	v_fmamk_f32 v169, v68, 0x3fb8aa3b, v172
	v_exp_f32_e32 v164, v169
	v_fmamk_f32 v169, v69, 0x3fb8aa3b, v172
	v_exp_f32_e32 v165, v169
	v_fmamk_f32 v169, v70, 0x3fb8aa3b, v172
	v_exp_f32_e32 v166, v169
	v_fmamk_f32 v169, v71, 0x3fb8aa3b, v172
	v_exp_f32_e32 v167, v169
	v_cvt_pk_bf16_f32 v64, v160, v161
	v_cvt_pk_bf16_f32 v65, v162, v163
	v_cvt_pk_bf16_f32 v66, v164, v165
	v_cvt_pk_bf16_f32 v67, v166, v167
	s_nop 0
	s_waitcnt lgkmcnt(6)
	v_mfma_f32_32x32x16_bf16 v[48:63], v[178:181], v[64:67], v[48:63]
	ds_read_b64_tr_b16 v[178:179], v177 offset:39936
	ds_read_b64_tr_b16 v[180:181], v177 offset:42496
	v_add_f32_e32 v190, v160, v162
	v_add_f32_e32 v191, v161, v163
	v_add_f32_e32 v190, v190, v164
	v_add_f32_e32 v191, v191, v165
	v_add_f32_e32 v190, v190, v166
	v_add_f32_e32 v191, v191, v167
	v_fmamk_f32 v169, v72, 0x3fb8aa3b, v172
	v_exp_f32_e32 v160, v169
	v_fmamk_f32 v169, v73, 0x3fb8aa3b, v172
	v_exp_f32_e32 v161, v169
	s_waitcnt lgkmcnt(6)
	v_mfma_f32_32x32x16_bf16 v[32:47], v[182:185], v[64:67], v[32:47]
	ds_read_b64_tr_b16 v[182:183], v177 offset:40000
	ds_read_b64_tr_b16 v[184:185], v177 offset:42560
	v_fmamk_f32 v169, v74, 0x3fb8aa3b, v172
	v_exp_f32_e32 v162, v169
	v_fmamk_f32 v169, v75, 0x3fb8aa3b, v172
	v_exp_f32_e32 v163, v169
	s_waitcnt lgkmcnt(6)
	v_mfma_f32_32x32x16_bf16 v[16:31], v[186:189], v[64:67], v[16:31]
	ds_read_b64_tr_b16 v[186:187], v177 offset:40064
	ds_read_b64_tr_b16 v[188:189], v177 offset:42624
	v_fmamk_f32 v169, v76, 0x3fb8aa3b, v172
	v_exp_f32_e32 v164, v169
	v_fmamk_f32 v169, v77, 0x3fb8aa3b, v172
	v_exp_f32_e32 v165, v169
	s_waitcnt lgkmcnt(6)
	v_mfma_f32_32x32x16_bf16 v[0:15], v[198:201], v[64:67], v[0:15]
	ds_read_b64_tr_b16 v[198:199], v177 offset:40128
	ds_read_b64_tr_b16 v[200:201], v177 offset:42688
	v_fmamk_f32 v169, v78, 0x3fb8aa3b, v172
	v_exp_f32_e32 v166, v169
	v_fmamk_f32 v169, v79, 0x3fb8aa3b, v172
	v_exp_f32_e32 v167, v169
	v_cvt_pk_bf16_f32 v72, v160, v161
	v_cvt_pk_bf16_f32 v73, v162, v163
	v_cvt_pk_bf16_f32 v74, v164, v165
	v_cvt_pk_bf16_f32 v75, v166, v167
	s_nop 0
	s_waitcnt lgkmcnt(6)
	v_mfma_f32_32x32x16_bf16 v[48:63], v[178:181], v[72:75], v[48:63]
	ds_read_b64_tr_b16 v[178:179], v177 offset:45056
	ds_read_b64_tr_b16 v[180:181], v177 offset:47616
	v_add_f32_e32 v190, v190, v160
	v_add_f32_e32 v191, v191, v161
	v_add_f32_e32 v190, v190, v162
	v_add_f32_e32 v191, v191, v163
	v_add_f32_e32 v190, v190, v164
	v_add_f32_e32 v191, v191, v165
	v_add_f32_e32 v190, v190, v166
	v_add_f32_e32 v191, v191, v167
	v_fmamk_f32 v169, v80, 0x3fb8aa3b, v172
	v_exp_f32_e32 v160, v169
	v_fmamk_f32 v169, v81, 0x3fb8aa3b, v172
	v_exp_f32_e32 v161, v169
	s_waitcnt lgkmcnt(6)
	v_mfma_f32_32x32x16_bf16 v[32:47], v[182:185], v[72:75], v[32:47]
	ds_read_b64_tr_b16 v[182:183], v177 offset:45120
	ds_read_b64_tr_b16 v[184:185], v177 offset:47680
	v_fmamk_f32 v169, v82, 0x3fb8aa3b, v172
	v_exp_f32_e32 v162, v169
	v_fmamk_f32 v169, v83, 0x3fb8aa3b, v172
	v_exp_f32_e32 v163, v169
	s_waitcnt lgkmcnt(6)
	v_mfma_f32_32x32x16_bf16 v[16:31], v[186:189], v[72:75], v[16:31]
	ds_read_b64_tr_b16 v[186:187], v177 offset:45184
	ds_read_b64_tr_b16 v[188:189], v177 offset:47744
	v_fmamk_f32 v169, v84, 0x3fb8aa3b, v172
	v_exp_f32_e32 v164, v169
	v_fmamk_f32 v169, v85, 0x3fb8aa3b, v172
	v_exp_f32_e32 v165, v169
	s_waitcnt lgkmcnt(6)
	v_mfma_f32_32x32x16_bf16 v[0:15], v[198:201], v[72:75], v[0:15]
	ds_read_b64_tr_b16 v[198:199], v177 offset:45248
	ds_read_b64_tr_b16 v[200:201], v177 offset:47808
	v_fmamk_f32 v169, v86, 0x3fb8aa3b, v172
	v_exp_f32_e32 v166, v169
	v_fmamk_f32 v169, v87, 0x3fb8aa3b, v172
	v_exp_f32_e32 v167, v169
	v_cvt_pk_bf16_f32 v80, v160, v161
	v_cvt_pk_bf16_f32 v81, v162, v163
	v_cvt_pk_bf16_f32 v82, v164, v165
	v_cvt_pk_bf16_f32 v83, v166, v167
	s_nop 0
	s_waitcnt lgkmcnt(6)
	v_mfma_f32_32x32x16_bf16 v[48:63], v[178:181], v[80:83], v[48:63]
	ds_read_b64_tr_b16 v[178:179], v177 offset:50176
	ds_read_b64_tr_b16 v[180:181], v177 offset:52736
	v_add_f32_e32 v190, v190, v160
	v_add_f32_e32 v191, v191, v161
	v_add_f32_e32 v190, v190, v162
	v_add_f32_e32 v191, v191, v163
	v_add_f32_e32 v190, v190, v164
	v_add_f32_e32 v191, v191, v165
	v_add_f32_e32 v190, v190, v166
	v_add_f32_e32 v191, v191, v167
	v_fmamk_f32 v169, v88, 0x3fb8aa3b, v172
	v_exp_f32_e32 v160, v169
	v_fmamk_f32 v169, v89, 0x3fb8aa3b, v172
	v_exp_f32_e32 v161, v169
	s_waitcnt lgkmcnt(6)
	v_mfma_f32_32x32x16_bf16 v[32:47], v[182:185], v[80:83], v[32:47]
	ds_read_b64_tr_b16 v[182:183], v177 offset:50240
	ds_read_b64_tr_b16 v[184:185], v177 offset:52800
	v_fmamk_f32 v169, v90, 0x3fb8aa3b, v172
	v_exp_f32_e32 v162, v169
	v_fmamk_f32 v169, v91, 0x3fb8aa3b, v172
	v_exp_f32_e32 v163, v169
	s_waitcnt lgkmcnt(6)
	v_mfma_f32_32x32x16_bf16 v[16:31], v[186:189], v[80:83], v[16:31]
	ds_read_b64_tr_b16 v[186:187], v177 offset:50304
	ds_read_b64_tr_b16 v[188:189], v177 offset:52864
	v_fmamk_f32 v169, v92, 0x3fb8aa3b, v172
	v_exp_f32_e32 v164, v169
	v_fmamk_f32 v169, v93, 0x3fb8aa3b, v172
	v_exp_f32_e32 v165, v169
	s_waitcnt lgkmcnt(6)
	v_mfma_f32_32x32x16_bf16 v[0:15], v[198:201], v[80:83], v[0:15]
	ds_read_b64_tr_b16 v[198:199], v177 offset:50368
	ds_read_b64_tr_b16 v[200:201], v177 offset:52928
	v_fmamk_f32 v169, v94, 0x3fb8aa3b, v172
	v_exp_f32_e32 v166, v169
	v_fmamk_f32 v169, v95, 0x3fb8aa3b, v172
	v_exp_f32_e32 v167, v169
	v_cvt_pk_bf16_f32 v88, v160, v161
	v_cvt_pk_bf16_f32 v89, v162, v163
	v_cvt_pk_bf16_f32 v90, v164, v165
	v_cvt_pk_bf16_f32 v91, v166, v167
	s_nop 0
	s_waitcnt lgkmcnt(6)
	v_mfma_f32_32x32x16_bf16 v[48:63], v[178:181], v[88:91], v[48:63]
	v_add_f32_e32 v190, v190, v160
	v_add_f32_e32 v191, v191, v161
	v_add_f32_e32 v190, v190, v162
	v_add_f32_e32 v191, v191, v163
	v_add_f32_e32 v190, v190, v164
	v_add_f32_e32 v191, v191, v165
	v_add_f32_e32 v190, v190, v166
	v_add_f32_e32 v191, v191, v167
	s_waitcnt lgkmcnt(4)
	v_mfma_f32_32x32x16_bf16 v[32:47], v[182:185], v[88:91], v[32:47]
	s_waitcnt lgkmcnt(2)
	v_mfma_f32_32x32x16_bf16 v[16:31], v[186:189], v[88:91], v[16:31]
	s_waitcnt lgkmcnt(0)
	v_mfma_f32_32x32x16_bf16 v[0:15], v[198:201], v[88:91], v[0:15]
	v_add_f32_e32 v176, v190, v191
	v_mov_b32_e32 v80, v174
	s_branch .Lattn2_tail
